# v10: GEMM first K iteration peeled with C=0 (no per-tile accumulator zeroing); GLA-B loop tail: next-next V fragments loaded in place after use, gating/staging waits recounted
# speedup vs baseline: 1.0555x; 1.0048x over previous
.Latt_u_noS:
	s_add_i32 s49, s49, 1
	s_cmp_gt_u32 s49, s47
	s_cbranch_scc1 .LBB0_44
	s_barrier
	s_branch .Latt_u_loop
	s_nop 0
	s_nop 0
	s_nop 0
	s_nop 0
	s_nop 0
	s_nop 0
	s_nop 0
	s_nop 0
	s_nop 0
	s_nop 0
	s_nop 0
	s_nop 0
	s_nop 0
	s_nop 0
	s_nop 0
	s_nop 0
	s_nop 0
	s_nop 0
	s_nop 0
	s_nop 0
	s_nop 0
	s_nop 0
	s_nop 0
	s_nop 0
	s_nop 0
	s_nop 0
	s_nop 0
	s_nop 0
	s_nop 0
	s_nop 0
	s_nop 0
	s_nop 0
	s_nop 0
	s_nop 0
	s_nop 0
	s_nop 0
	s_nop 0
	s_nop 0
	s_nop 0
	s_nop 0
	s_nop 0
	s_nop 0
	s_nop 0
	s_nop 0
	s_nop 0
	s_nop 0
	s_nop 0
	s_nop 0
	s_nop 0
	s_nop 0
	s_nop 0
	s_nop 0
	s_nop 0
	s_nop 0
	s_nop 0
	s_nop 0
.LBB0_75:
	v_readlane_b32 s54, v255, 12
	s_mov_b64 s[8:9], 0
	v_readlane_b32 s55, v255, 13
	v_readlane_b32 s27, v255, 31

.LBB0_108:
	s_or_b64 exec, exec, s[44:45]
	s_ashr_i32 s55, s54, 31
	s_lshl_b64 s[44:45], s[54:55], 10
	s_add_u32 s42, s62, s50
	s_addc_u32 s43, 0, s51
	s_add_u32 s42, s42, s44
	v_and_b32_e32 v176, 31, v148
	s_addc_u32 s43, s43, s45
	v_or_b32_e32 v82, s42, v176
	v_mov_b32_e32 v83, s43
	v_lshlrev_b64 v[82:83], 7, v[82:83]
	v_lshl_add_u64 v[82:83], s[28:29], 0, v[82:83]
	v_mov_b32_e32 v81, v0
	v_lshl_add_u64 v[132:133], v[82:83], 0, v[80:81]
	s_lshl_b32 s42, s56, 20
	s_mov_b32 s43, s59
	v_lshl_add_u64 v[80:81], v[132:133], 0, s[42:43]
	global_load_dwordx4 v[92:95], v[80:81], off
	global_load_dwordx4 v[88:91], v[80:81], off offset:32
	global_load_dwordx4 v[84:87], v[80:81], off offset:64
	s_nop 0
	global_load_dwordx4 v[80:83], v[80:81], off offset:96
	v_add_u32_e32 v116, 0, v14
	v_mul_lo_u32 v15, v168, s82
	v_add_u32_e32 v117, v116, v15
	v_mul_lo_u32 v165, v170, s82
	s_waitcnt vmcnt(7)
	ds_write_b128 v117, v[100:103]
	v_add_u32_e32 v100, v116, v165
	s_movk_i32 s42, 0x110
	s_waitcnt vmcnt(6)
	ds_write_b128 v100, v[96:99]
	v_add_u32_e32 v96, 0, v172
	v_mul_lo_u32 v173, v151, s42
	v_mul_lo_u32 v228, v152, s42
	v_add_u32_e32 v97, v96, v173
	v_add_u32_e32 v96, v96, v228
	s_waitcnt vmcnt(5)
	ds_write_b128 v97, v[108:111] offset:18432
	s_waitcnt vmcnt(4)
	ds_write_b128 v96, v[104:107] offset:18432
	s_and_saveexec_b64 s[42:43], vcc
	v_lshl_add_u32 v96, v148, 2, 0
	ds_write_b32 v96, v1 offset:35840
	s_or_b64 exec, exec, s[42:43]
	s_or_b32 s55, s64, 1
	s_or_b32 s42, s55, s54
	s_ashr_i32 s43, s42, 31
	s_lshl_b64 s[56:57], s[42:43], 9
	s_or_b64 s[56:57], s[56:57], s[58:59]
	v_lshl_add_u64 v[96:97], s[56:57], 0, v[168:169]
	s_lshl_b32 s65, s55, 6
	v_lshlrev_b64 v[96:97], 7, v[96:97]
	v_lshl_add_u64 v[98:99], s[56:57], 0, v[170:171]
	v_lshl_add_u64 v[96:97], v[166:167], 0, v[96:97]
	v_lshlrev_b64 v[98:99], 7, v[98:99]
	s_or_b32 s43, s65, s63
	v_lshl_add_u64 v[98:99], v[166:167], 0, v[98:99]
	global_load_dwordx4 v[116:119], v[96:97], off
	global_load_dwordx4 v[120:123], v[98:99], off
	v_add_u32_e32 v96, s43, v151
	v_ashrrev_i32_e32 v97, 31, v96
	v_add_u32_e32 v98, s43, v152
	v_lshlrev_b64 v[96:97], 10, v[96:97]
	v_ashrrev_i32_e32 v99, 31, v98
	v_lshl_add_u64 v[96:97], v[174:175], 0, v[96:97]
	v_lshlrev_b64 v[98:99], 10, v[98:99]
	v_lshl_add_u64 v[98:99], v[174:175], 0, v[98:99]
	global_load_dwordx4 v[124:127], v[96:97], off
	global_load_dwordx4 v[128:131], v[98:99], off
	s_lshl_b32 s42, s42, 9
	s_or_b32 s42, s42, s58
	v_add_u32_e32 v96, s42, v148
	v_ashrrev_i32_e32 v97, 31, v96
	v_lshl_add_u64 v[96:97], v[96:97], 2, s[40:41]
	global_load_dword v1, v[96:97], off
	global_load_dword v1, v[96:97], off
	global_load_dword v1, v[96:97], off
	global_load_dword v1, v[96:97], off
	global_load_dword v1, v[96:97], off
	s_lshl_b32 s42, s55, 17
	s_mov_b32 s43, s59
	v_lshl_add_u64 v[96:97], v[132:133], 0, s[42:43]
	global_load_dwordx4 v[132:135], v[96:97], off
	global_load_dwordx4 v[136:139], v[96:97], off offset:32
	global_load_dwordx4 v[140:143], v[96:97], off offset:64
	global_load_dwordx4 v[144:147], v[96:97], off offset:96
	s_lshl_b32 s56, s60, 3
	s_lshl_b32 s66, s60, 9
	s_lshl_b32 s67, s60, 12
	s_or_b32 s55, s56, 2
	s_lshl_b32 s56, s60, 20
	s_add_i32 s60, s64, 8
	s_lshl_b32 s64, s62, 1
	v_lshlrev_b32_e32 v98, 3, v148
	s_add_u32 s42, s26, s64
	s_addc_u32 s43, s27, 0
	v_and_b32_e32 v96, 0xf8, v98
	v_lshlrev_b32_e32 v96, 1, v96
	v_mov_b32_e32 v97, v0
	s_add_u32 s64, s31, s64
	v_lshl_add_u64 v[178:179], s[42:43], 0, v[96:97]
	v_lshlrev_b32_e32 v96, 4, v176
	s_addc_u32 s65, s35, 0
	s_add_i32 s66, s66, s63
	s_lshl_b32 s61, s61, 14
	s_or_b32 s63, s58, s67
	v_lshl_add_u64 v[180:181], s[64:65], 0, v[96:97]
	v_add_u32_e32 v97, 0x400, v148
	s_or_b32 s61, s63, s61
	v_readlane_b32 s91, v255, 4
	v_add_u32_e32 v186, s61, v97
	s_lshl_b32 s61, s39, 7
	v_lshlrev_b32_e32 v99, 3, v149
	v_add_u32_e32 v98, s91, v96
	v_ashrrev_i32_e32 v96, 5, v148
	v_mul_u32_u24_e32 v103, 0x210, v176
	s_movk_i32 s64, 0x210
	s_and_b32 s61, s61, 0x600
	v_add3_u32 v232, s91, v103, v99
	v_mul_lo_u32 v103, v96, s64
	v_add_u32_e32 v107, s66, v152
	v_add_u32_e32 v96, s66, v96
	s_add_u32 s44, s50, s44
	v_ashrrev_i32_e32 v101, 5, v97
	v_add_u32_e32 v182, 0x80, v107
	v_add_u32_e32 v107, s66, v151
	v_ashrrev_i32_e32 v97, 31, v96
	s_addc_u32 s45, s51, s45
	v_add_u32_e32 v184, 0x80, v107
	v_lshlrev_b64 v[96:97], 11, v[96:97]
	v_lshlrev_b32_e32 v107, 4, v176
	s_add_u32 s44, s44, s62
	v_mov_b32_e32 v177, v0
	v_or3_b32 v96, v96, s61, v107
	s_addc_u32 s45, s45, 0
	v_lshl_add_u64 v[188:189], s[36:37], 0, v[96:97]
	v_lshl_add_u64 v[96:97], s[44:45], 0, v[176:177]
	s_mov_b32 s57, s59
	v_lshlrev_b64 v[96:97], 7, v[96:97]
	v_and_b32_e32 v108, 32, v148
	v_lshl_add_u64 v[96:97], s[56:57], 0, v[96:97]
	v_lshrrev_b32_e32 v108, 1, v108
	v_ashrrev_i32_e32 v100, 5, v153
	v_or_b32_e32 v96, v96, v108
	v_lshl_add_u64 v[190:191], s[52:53], 0, v[96:97]
	v_add_u32_e32 v96, s66, v100
	v_add_u32_e32 v102, 0x600, v148
	v_ashrrev_i32_e32 v97, 31, v96
	s_waitcnt lgkmcnt(0)
	s_barrier
	v_ashrrev_i32_e32 v102, 5, v102
	v_lshlrev_b64 v[96:97], 11, v[96:97]
	v_add_u32_e32 v99, 0x4200, v232
	v_mul_lo_u32 v104, v100, s64
	v_mul_lo_u32 v105, v101, s64
	v_mul_lo_u32 v106, v102, s64
	v_or3_b32 v96, v96, s61, v107
	v_cmp_gt_u32_e64 s[42:43], 32, v150
	v_lshlrev_b32_e32 v229, 2, v148
	v_mul_u32_u24_e32 v230, 0x90, v176
	v_mul_u32_u24_e32 v231, 0x110, v176
	v_lshl_add_u32 v233, v149, 4, 0
	v_lshl_add_u64 v[192:193], s[36:37], 0, v[96:97]
	v_add_u32_e32 v194, s66, v102
	v_add_u32_e32 v196, s66, v101
	s_mov_b64 s[56:57], 0
	v_add_u32_e32 v177, s24, v99
	v_add_u32_e32 v234, v98, v103
	v_add_u32_e32 v235, v98, v104
	v_add_u32_e32 v236, v98, v105
	v_add_u32_e32 v237, v98, v106
	s_branch .LBB0_115
.LBB0_114:
	s_waitcnt lgkmcnt(0)
	s_barrier
	ds_read_b128 v[80:83], v234
	s_waitcnt vmcnt(8)
	v_lshlrev_b32_e32 v86, 16, v160
	v_and_b32_e32 v87, 0xffff0000, v160
	v_lshlrev_b32_e32 v88, 16, v162
	v_and_b32_e32 v89, 0xffff0000, v162
	s_waitcnt lgkmcnt(0)
	v_lshlrev_b32_e32 v84, 16, v80
	v_and_b32_e32 v85, 0xffff0000, v80
	v_pk_mul_f32 v[84:85], v[84:85], v[86:87]
	v_lshlrev_b32_e32 v80, 16, v81
	v_and_b32_e32 v81, 0xffff0000, v81
	v_lshlrev_b32_e32 v86, 16, v161
	v_and_b32_e32 v87, 0xffff0000, v161
	v_pk_mul_f32 v[86:87], v[80:81], v[86:87]
	v_lshlrev_b32_e32 v80, 16, v82
	v_and_b32_e32 v81, 0xffff0000, v82
	v_pk_mul_f32 v[88:89], v[80:81], v[88:89]
	v_lshlrev_b32_e32 v80, 16, v83
	v_and_b32_e32 v81, 0xffff0000, v83
	v_lshlrev_b32_e32 v82, 16, v163
	v_and_b32_e32 v83, 0xffff0000, v163
	v_pk_mul_f32 v[90:91], v[80:81], v[82:83]
	v_cvt_pk_bf16_f32 v80, v84, v85
	v_add_co_u32_e64 v84, s[44:45], s84, v204
	v_cvt_pk_bf16_f32 v81, v86, v87
	v_cvt_pk_bf16_f32 v82, v88, v89
	v_cvt_pk_bf16_f32 v83, v90, v91
	v_addc_co_u32_e64 v85, s[44:45], 0, v205, s[44:45]
	global_store_dwordx4 v[84:85], v[80:83], off
	ds_read_b128 v[80:83], v235
	s_waitcnt vmcnt(8)
	v_lshlrev_b32_e32 v86, 16, v156
	v_and_b32_e32 v87, 0xffff0000, v156
	v_lshlrev_b32_e32 v88, 16, v158
	v_and_b32_e32 v89, 0xffff0000, v158
	s_waitcnt lgkmcnt(0)
	v_lshlrev_b32_e32 v84, 16, v80
	v_and_b32_e32 v85, 0xffff0000, v80
	v_pk_mul_f32 v[84:85], v[84:85], v[86:87]
	v_lshlrev_b32_e32 v80, 16, v81
	v_and_b32_e32 v81, 0xffff0000, v81
	v_lshlrev_b32_e32 v86, 16, v157
	v_and_b32_e32 v87, 0xffff0000, v157
	v_pk_mul_f32 v[86:87], v[80:81], v[86:87]
	v_lshlrev_b32_e32 v80, 16, v82
	v_and_b32_e32 v81, 0xffff0000, v82
	v_pk_mul_f32 v[88:89], v[80:81], v[88:89]
	v_lshlrev_b32_e32 v80, 16, v83
	v_and_b32_e32 v81, 0xffff0000, v83
	v_lshlrev_b32_e32 v82, 16, v159
	v_and_b32_e32 v83, 0xffff0000, v159
	v_pk_mul_f32 v[90:91], v[80:81], v[82:83]
	v_cvt_pk_bf16_f32 v80, v84, v85
	v_add_co_u32_e64 v84, s[44:45], s84, v202
	v_cvt_pk_bf16_f32 v81, v86, v87
	v_cvt_pk_bf16_f32 v82, v88, v89
	v_cvt_pk_bf16_f32 v83, v90, v91
	v_addc_co_u32_e64 v85, s[44:45], 0, v203, s[44:45]
	global_store_dwordx4 v[84:85], v[80:83], off
	ds_read_b128 v[80:83], v236
	s_waitcnt vmcnt(8)
	v_lshlrev_b32_e32 v86, 16, v152
	v_and_b32_e32 v87, 0xffff0000, v152
	v_lshlrev_b32_e32 v88, 16, v154
	v_and_b32_e32 v89, 0xffff0000, v154
	s_waitcnt lgkmcnt(0)
	v_lshlrev_b32_e32 v84, 16, v80
	v_and_b32_e32 v85, 0xffff0000, v80
	v_pk_mul_f32 v[84:85], v[84:85], v[86:87]
	v_lshlrev_b32_e32 v80, 16, v81
	v_and_b32_e32 v81, 0xffff0000, v81
	v_lshlrev_b32_e32 v86, 16, v153
	v_and_b32_e32 v87, 0xffff0000, v153
	v_pk_mul_f32 v[86:87], v[80:81], v[86:87]
	v_lshlrev_b32_e32 v80, 16, v82
	v_and_b32_e32 v81, 0xffff0000, v82
	v_pk_mul_f32 v[88:89], v[80:81], v[88:89]
	v_lshlrev_b32_e32 v80, 16, v83
	v_and_b32_e32 v81, 0xffff0000, v83
	v_lshlrev_b32_e32 v82, 16, v155
	v_and_b32_e32 v83, 0xffff0000, v155
	v_pk_mul_f32 v[90:91], v[80:81], v[82:83]
	v_cvt_pk_bf16_f32 v80, v84, v85
	v_cvt_pk_bf16_f32 v81, v86, v87
	v_cvt_pk_bf16_f32 v82, v88, v89
	v_cvt_pk_bf16_f32 v83, v90, v91
	v_lshl_add_u64 v[84:85], v[180:181], 0, v[200:201]
	global_store_dwordx4 v[84:85], v[80:83], off
	ds_read_b128 v[80:83], v237
	s_waitcnt vmcnt(8)
	v_lshlrev_b32_e32 v86, 16, v148
	v_and_b32_e32 v87, 0xffff0000, v148
	v_lshlrev_b32_e32 v88, 16, v150
	v_and_b32_e32 v89, 0xffff0000, v150
	s_waitcnt lgkmcnt(0)
	v_lshlrev_b32_e32 v84, 16, v80
	v_and_b32_e32 v85, 0xffff0000, v80
	v_pk_mul_f32 v[84:85], v[84:85], v[86:87]
	v_lshlrev_b32_e32 v80, 16, v81
	v_and_b32_e32 v81, 0xffff0000, v81
	v_lshlrev_b32_e32 v86, 16, v149
	v_and_b32_e32 v87, 0xffff0000, v149
	v_pk_mul_f32 v[86:87], v[80:81], v[86:87]
	v_lshlrev_b32_e32 v80, 16, v82
	v_and_b32_e32 v81, 0xffff0000, v82
	v_pk_mul_f32 v[88:89], v[80:81], v[88:89]
	v_lshlrev_b32_e32 v80, 16, v83
	v_and_b32_e32 v81, 0xffff0000, v83
	v_lshlrev_b32_e32 v82, 16, v151
	v_and_b32_e32 v83, 0xffff0000, v151
	v_pk_mul_f32 v[90:91], v[80:81], v[82:83]
	v_cvt_pk_bf16_f32 v80, v84, v85
	v_cvt_pk_bf16_f32 v81, v86, v87
	v_cvt_pk_bf16_f32 v82, v88, v89
	v_cvt_pk_bf16_f32 v83, v90, v91
	v_lshl_add_u64 v[84:85], v[180:181], 0, v[198:199]
	global_store_dwordx4 v[84:85], v[80:83], off
	v_lshl_add_u64 v[246:247], v[190:191], 0, s[56:57]
	v_mov_b64_e32 v[84:85], v[140:141]
	v_mov_b64_e32 v[80:81], v[144:145]
	v_mov_b64_e32 v[88:89], v[136:137]
	v_mov_b64_e32 v[92:93], v[132:133]
	v_mov_b64_e32 v[82:83], v[146:147]
	v_mov_b64_e32 v[86:87], v[142:143]
	v_mov_b64_e32 v[90:91], v[138:139]
	v_mov_b64_e32 v[94:95], v[134:135]
	global_load_dwordx4 v[132:135], v[246:247], off offset:-64
	global_load_dwordx4 v[136:139], v[246:247], off offset:-32
	global_load_dwordx4 v[140:143], v[246:247], off
	global_load_dwordx4 v[144:147], v[246:247], off offset:32
	s_add_u32 s56, s56, 0x20000
	s_addc_u32 s57, s57, 0
	s_add_i32 s55, s55, 1
	v_add_u32_e32 v182, 64, v182
	v_add_u32_e32 v184, 64, v184
	v_add_u32_e32 v186, 0x200, v186
	v_add_u32_e32 v194, 64, v194
	v_add_u32_e32 v196, 64, v196
	s_cmp_eq_u32 s56, 0x100000
	s_cbranch_scc0 .Lgla6_cont
	s_waitcnt vmcnt(0)
	s_branch .LBB0_100
.Lgla6_cont:
.LBB0_115:
	s_add_i32 s44, s55, -2
	v_lshl_add_u64 v[204:205], v[188:189], 0, s[56:57]
	s_and_b32 s61, s44, 1
	v_add_co_u32_e64 v96, s[44:45], s83, v204
	v_lshl_add_u64 v[202:203], v[192:193], 0, s[56:57]
	s_nop 0
	v_addc_co_u32_e64 v97, s[44:45], 0, v205, s[44:45]
	global_load_dwordx4 v[160:163], v[96:97], off
	v_add_co_u32_e64 v96, s[44:45], s83, v202
	v_ashrrev_i32_e32 v197, 31, v196
	s_nop 0
	v_addc_co_u32_e64 v97, s[44:45], 0, v203, s[44:45]
	v_lshlrev_b64 v[200:201], 11, v[196:197]
	v_ashrrev_i32_e32 v195, 31, v194
	global_load_dwordx4 v[156:159], v[96:97], off
	v_lshl_add_u64 v[96:97], v[178:179], 0, v[200:201]
	v_lshlrev_b64 v[198:199], 11, v[194:195]
	s_mul_i32 s62, s61, 0x8e00
	global_load_dwordx4 v[152:155], v[96:97], off
	v_lshl_add_u64 v[96:97], v[178:179], 0, v[198:199]
	global_load_dwordx4 v[148:151], v[96:97], off
	v_add_u32_e32 v96, s62, v233
	ds_read_b128 v[98:101], v96 offset:35840
	ds_read_b128 v[102:105], v96 offset:35872
	ds_read_b128 v[106:109], v96 offset:35904
	ds_read_b128 v[238:241], v96 offset:35936
	v_add_u32_e32 v97, v96, v230
	s_waitcnt lgkmcnt(3)
	v_pk_mul_f32 v[66:67], v[100:101], v[66:67]
	s_waitcnt lgkmcnt(2)
	v_pk_mul_f32 v[68:69], v[102:103], v[68:69]
	s_waitcnt lgkmcnt(1)
	v_pk_mul_f32 v[72:73], v[106:107], v[72:73]
	s_waitcnt lgkmcnt(0)
	v_pk_mul_f32 v[76:77], v[238:239], v[76:77]
	v_pk_mul_f32 v[78:79], v[240:241], v[78:79]
	v_pk_mul_f32 v[74:75], v[108:109], v[74:75]
	v_pk_mul_f32 v[70:71], v[104:105], v[70:71]
	v_pk_mul_f32 v[64:65], v[98:99], v[64:65]
	ds_read_b128 v[98:101], v96 offset:35968
	ds_read_b128 v[102:105], v96 offset:36000
	ds_read_b128 v[106:109], v96 offset:36032
	ds_read_b128 v[238:241], v96 offset:36064
	v_add_u32_e32 v183, v96, v231
	s_waitcnt lgkmcnt(3)
	v_pk_mul_f32 v[50:51], v[100:101], v[50:51]
	s_waitcnt lgkmcnt(2)
	v_pk_mul_f32 v[52:53], v[102:103], v[52:53]
	s_waitcnt lgkmcnt(1)
	v_pk_mul_f32 v[56:57], v[106:107], v[56:57]
	s_waitcnt lgkmcnt(0)
	v_pk_mul_f32 v[60:61], v[238:239], v[60:61]
	v_pk_mul_f32 v[62:63], v[240:241], v[62:63]
	v_pk_mul_f32 v[58:59], v[108:109], v[58:59]
	v_pk_mul_f32 v[54:55], v[104:105], v[54:55]
	v_pk_mul_f32 v[48:49], v[98:99], v[48:49]
	ds_read_b128 v[98:101], v96 offset:36096
	ds_read_b128 v[102:105], v96 offset:36128
	ds_read_b128 v[106:109], v96 offset:36160
	ds_read_b128 v[238:241], v96 offset:36192
	s_lshl_b32 s44, s61, 11
	s_waitcnt lgkmcnt(3)
	v_pk_mul_f32 v[34:35], v[100:101], v[34:35]
	s_waitcnt lgkmcnt(2)
	v_pk_mul_f32 v[36:37], v[102:103], v[36:37]
	s_waitcnt lgkmcnt(1)
	v_pk_mul_f32 v[40:41], v[106:107], v[40:41]
	s_waitcnt lgkmcnt(0)
	v_pk_mul_f32 v[44:45], v[238:239], v[44:45]
	v_pk_mul_f32 v[46:47], v[240:241], v[46:47]
	v_pk_mul_f32 v[42:43], v[108:109], v[42:43]
	v_pk_mul_f32 v[38:39], v[104:105], v[38:39]
	v_pk_mul_f32 v[32:33], v[98:99], v[32:33]
	ds_read_b128 v[98:101], v96 offset:36224
	ds_read_b128 v[102:105], v96 offset:36256
	ds_read_b128 v[106:109], v96 offset:36288
	ds_read_b128 v[238:241], v96 offset:36320
	s_add_i32 s61, s44, 0
	s_waitcnt lgkmcnt(3)
	v_pk_mul_f32 v[18:19], v[100:101], v[18:19]
	s_waitcnt lgkmcnt(2)
	v_pk_mul_f32 v[20:21], v[102:103], v[20:21]
	v_pk_mul_f32 v[22:23], v[104:105], v[22:23]
	v_pk_mul_f32 v[16:17], v[98:99], v[16:17]
	s_waitcnt lgkmcnt(0)
	v_mul_f32_e64 v28, v238, v28
	v_mul_f32_e64 v29, v239, v29
	v_mul_f32_e64 v24, v106, v24
	v_mul_f32_e64 v25, v107, v25
	v_pk_mul_f32 v[30:31], v[240:241], v[30:31]
	v_pk_mul_f32 v[26:27], v[108:109], v[26:27]
	s_add_i32 s61, s61, 0x11c00
	s_lshl_b32 s44, s24, 2
	s_add_i32 s44, s61, s44
	ds_read_b128 v[98:101], v97
	ds_read_b128 v[102:105], v97 offset:4608
	ds_read_b128 v[210:213], v97 offset:9216
	ds_read_b128 v[214:217], v97 offset:13824
	ds_read_b128 v[246:249], v97 offset:32
	ds_read_b128 v[250:253], v97 offset:4640
	s_waitcnt vmcnt(15) lgkmcnt(5)
	v_mfma_f32_32x32x16_bf16 v[64:79], v[98:101], v[92:95], v[64:79]
	ds_read_b128 v[98:101], v97 offset:9248
	s_waitcnt lgkmcnt(5)
	v_mfma_f32_32x32x16_bf16 v[48:63], v[102:105], v[92:95], v[48:63]
	ds_read_b128 v[102:105], v97 offset:13856
	s_waitcnt lgkmcnt(5)
	v_mfma_f32_32x32x16_bf16 v[32:47], v[210:213], v[92:95], v[32:47]
	ds_read_b128 v[210:213], v97 offset:64
	s_waitcnt lgkmcnt(5)
	v_mfma_f32_32x32x16_bf16 v[16:31], v[214:217], v[92:95], v[16:31]
	ds_read_b128 v[214:217], v97 offset:4672
	s_waitcnt vmcnt(14) lgkmcnt(5)
	v_mfma_f32_32x32x16_bf16 v[64:79], v[246:249], v[88:91], v[64:79]
	ds_read_b128 v[246:249], v97 offset:9280
	s_waitcnt lgkmcnt(5)
	v_mfma_f32_32x32x16_bf16 v[48:63], v[250:253], v[88:91], v[48:63]
	ds_read_b128 v[250:253], v97 offset:13888
	s_waitcnt lgkmcnt(5)
	v_mfma_f32_32x32x16_bf16 v[32:47], v[98:101], v[88:91], v[32:47]
	ds_read_b128 v[98:101], v97 offset:96
	s_waitcnt lgkmcnt(5)
	v_mfma_f32_32x32x16_bf16 v[16:31], v[102:105], v[88:91], v[16:31]
	ds_read_b128 v[102:105], v97 offset:4704
	s_waitcnt vmcnt(13) lgkmcnt(5)
	v_mfma_f32_32x32x16_bf16 v[64:79], v[210:213], v[84:87], v[64:79]
	ds_read_b128 v[210:213], v97 offset:9312
	s_waitcnt lgkmcnt(5)
	v_mfma_f32_32x32x16_bf16 v[48:63], v[214:217], v[84:87], v[48:63]
	ds_read_b128 v[214:217], v97 offset:13920
	s_waitcnt lgkmcnt(5)
	v_mfma_f32_32x32x16_bf16 v[32:47], v[246:249], v[84:87], v[32:47]
	s_waitcnt lgkmcnt(4)
	v_mfma_f32_32x32x16_bf16 v[16:31], v[250:253], v[84:87], v[16:31]
	s_waitcnt vmcnt(12) lgkmcnt(3)
	v_mfma_f32_32x32x16_bf16 v[64:79], v[98:101], v[80:83], v[64:79]
	s_waitcnt lgkmcnt(2)
	v_mfma_f32_32x32x16_bf16 v[48:63], v[102:105], v[80:83], v[48:63]
	s_waitcnt lgkmcnt(1)
	v_mfma_f32_32x32x16_bf16 v[32:47], v[210:213], v[80:83], v[32:47]
	s_waitcnt lgkmcnt(0)
	v_mfma_f32_32x32x16_bf16 v[16:31], v[214:217], v[80:83], v[16:31]
	ds_read_b128 v[246:249], v183 offset:18432
	ds_read_b128 v[250:253], v183 offset:27136
	ds_read_b128 v[210:213], v183 offset:18464
	ds_read_b128 v[214:217], v183 offset:27168
	s_nop 4
	v_cvt_pk_bf16_f32 v238, v64, v65
	v_cvt_pk_bf16_f32 v239, v66, v67
	v_cvt_pk_bf16_f32 v240, v68, v69
	v_cvt_pk_bf16_f32 v241, v70, v71
	v_cvt_pk_bf16_f32 v242, v72, v73
	v_cvt_pk_bf16_f32 v243, v74, v75
	v_cvt_pk_bf16_f32 v244, v76, v77
	v_cvt_pk_bf16_f32 v245, v78, v79
	s_waitcnt lgkmcnt(3)
	v_mfma_f32_32x32x16_bf16 v[96:111], v[238:241], v[246:249], 0
	s_waitcnt lgkmcnt(2)
	v_mfma_f32_32x32x16_bf16 v[80:95], v[238:241], v[250:253], 0
	v_cvt_pk_bf16_f32 v238, v48, v49
	v_cvt_pk_bf16_f32 v239, v50, v51
	v_cvt_pk_bf16_f32 v240, v52, v53
	v_cvt_pk_bf16_f32 v241, v54, v55
	ds_read_b128 v[246:249], v183 offset:18496
	ds_read_b128 v[250:253], v183 offset:27200
	s_waitcnt lgkmcnt(3)
	v_mfma_f32_32x32x16_bf16 v[96:111], v[242:245], v[210:213], v[96:111]
	s_waitcnt lgkmcnt(2)
	v_mfma_f32_32x32x16_bf16 v[80:95], v[242:245], v[214:217], v[80:95]
	v_cvt_pk_bf16_f32 v242, v56, v57
	v_cvt_pk_bf16_f32 v243, v58, v59
	v_cvt_pk_bf16_f32 v244, v60, v61
	v_cvt_pk_bf16_f32 v245, v62, v63
	ds_read_b128 v[210:213], v183 offset:18528
	ds_read_b128 v[214:217], v183 offset:27232
	s_waitcnt lgkmcnt(3)
	v_mfma_f32_32x32x16_bf16 v[96:111], v[238:241], v[246:249], v[96:111]
	s_waitcnt lgkmcnt(2)
	v_mfma_f32_32x32x16_bf16 v[80:95], v[238:241], v[250:253], v[80:95]
	v_cvt_pk_bf16_f32 v238, v32, v33
	v_cvt_pk_bf16_f32 v239, v34, v35
	v_cvt_pk_bf16_f32 v240, v36, v37
	v_cvt_pk_bf16_f32 v241, v38, v39
	ds_read_b128 v[246:249], v183 offset:18560
	ds_read_b128 v[250:253], v183 offset:27264
	s_waitcnt lgkmcnt(3)
	v_mfma_f32_32x32x16_bf16 v[96:111], v[242:245], v[210:213], v[96:111]
	s_waitcnt lgkmcnt(2)
	v_mfma_f32_32x32x16_bf16 v[80:95], v[242:245], v[214:217], v[80:95]
	v_cvt_pk_bf16_f32 v242, v40, v41
	v_cvt_pk_bf16_f32 v243, v42, v43
	v_cvt_pk_bf16_f32 v244, v44, v45
	v_cvt_pk_bf16_f32 v245, v46, v47
	ds_read_b128 v[210:213], v183 offset:18592
	ds_read_b128 v[214:217], v183 offset:27296
	s_waitcnt lgkmcnt(3)
	v_mfma_f32_32x32x16_bf16 v[96:111], v[238:241], v[246:249], v[96:111]
	s_waitcnt lgkmcnt(2)
	v_mfma_f32_32x32x16_bf16 v[80:95], v[238:241], v[250:253], v[80:95]
	v_cvt_pk_bf16_f32 v238, v16, v17
	v_cvt_pk_bf16_f32 v239, v18, v19
	v_cvt_pk_bf16_f32 v240, v20, v21
	v_cvt_pk_bf16_f32 v241, v22, v23
	ds_read_b128 v[246:249], v183 offset:18624
	ds_read_b128 v[250:253], v183 offset:27328
	s_waitcnt lgkmcnt(3)
	v_mfma_f32_32x32x16_bf16 v[96:111], v[242:245], v[210:213], v[96:111]
	s_waitcnt lgkmcnt(2)
	v_mfma_f32_32x32x16_bf16 v[80:95], v[242:245], v[214:217], v[80:95]
	v_cvt_pk_bf16_f32 v242, v24, v25
	v_cvt_pk_bf16_f32 v243, v26, v27
	v_cvt_pk_bf16_f32 v244, v28, v29
	v_cvt_pk_bf16_f32 v245, v30, v31
	ds_read_b128 v[210:213], v183 offset:18656
	ds_read_b128 v[214:217], v183 offset:27360
	s_waitcnt lgkmcnt(3)
	v_mfma_f32_32x32x16_bf16 v[96:111], v[238:241], v[246:249], v[96:111]
	s_waitcnt lgkmcnt(2)
	v_mfma_f32_32x32x16_bf16 v[80:95], v[238:241], v[250:253], v[80:95]
	s_waitcnt lgkmcnt(1)
	v_mfma_f32_32x32x16_bf16 v[96:111], v[242:245], v[210:213], v[96:111]
	s_waitcnt lgkmcnt(0)
	v_mfma_f32_32x32x16_bf16 v[80:95], v[242:245], v[214:217], v[80:95]
	v_lshl_add_u32 v183, v176, 2, s44
	s_nop 0
	s_nop 7
	v_mul_f32_e32 v185, v97, v97
	v_fmac_f32_e32 v185, v96, v96
	v_fmac_f32_e32 v185, v98, v98
	v_fmac_f32_e32 v185, v99, v99
	v_fmac_f32_e32 v185, v100, v100
	v_fmac_f32_e32 v185, v101, v101
	v_fmac_f32_e32 v185, v102, v102
	v_fmac_f32_e32 v185, v103, v103
	v_fmac_f32_e32 v185, v104, v104
	v_fmac_f32_e32 v185, v105, v105
	v_fmac_f32_e32 v185, v106, v106
	v_fmac_f32_e32 v185, v107, v107
	v_fmac_f32_e32 v185, v108, v108
	v_fmac_f32_e32 v185, v109, v109
	v_fmac_f32_e32 v185, v110, v110
	v_fmac_f32_e32 v185, v111, v111
	v_mov_b32_e32 v187, v185
	s_nop 1
	v_permlane32_swap_b32_e32 v185, v187
	s_and_saveexec_b64 s[44:45], s[42:43]
	v_add_f32_e32 v185, v185, v187
	ds_write_b32 v183, v185
	s_or_b64 exec, exec, s[44:45]
	v_mul_f32_e32 v185, v81, v81
	v_fmac_f32_e32 v185, v80, v80
	v_fmac_f32_e32 v185, v82, v82
	v_fmac_f32_e32 v185, v83, v83
	v_fmac_f32_e32 v185, v84, v84
	v_fmac_f32_e32 v185, v85, v85
	v_fmac_f32_e32 v185, v86, v86
	v_fmac_f32_e32 v185, v87, v87
	v_fmac_f32_e32 v185, v88, v88
	v_fmac_f32_e32 v185, v89, v89
	v_fmac_f32_e32 v185, v90, v90
	v_fmac_f32_e32 v185, v91, v91
	v_fmac_f32_e32 v185, v92, v92
	v_fmac_f32_e32 v185, v93, v93
	v_fmac_f32_e32 v185, v94, v94
	v_fmac_f32_e32 v185, v95, v95
	v_mov_b32_e32 v187, v185
	s_nop 1
	v_permlane32_swap_b32_e32 v185, v187
	s_and_saveexec_b64 s[44:45], s[42:43]
	v_add_f32_e32 v185, v185, v187
	ds_write_b32 v183, v185 offset:128
	s_or_b64 exec, exec, s[44:45]
	s_waitcnt lgkmcnt(0)
	s_barrier
	v_lshl_add_u32 v183, v176, 2, s61
	ds_read_b32 v210, v183
	ds_read_b32 v211, v183 offset:256
	ds_read_b32 v212, v183 offset:512
	ds_read_b32 v213, v183 offset:768
	ds_read_b32 v214, v183 offset:1024
	ds_read_b32 v215, v183 offset:1280
	ds_read_b32 v216, v183 offset:1536
	ds_read_b32 v217, v183 offset:1792
	ds_read_b32 v246, v183 offset:128
	ds_read_b32 v247, v183 offset:384
	ds_read_b32 v248, v183 offset:640
	ds_read_b32 v249, v183 offset:896
	ds_read_b32 v250, v183 offset:1152
	ds_read_b32 v251, v183 offset:1408
	ds_read_b32 v252, v183 offset:1664
	ds_read_b32 v253, v183 offset:1920
	s_add_i32 s44, s55, -1
	s_cmp_ge_u32 s44, s60
	s_waitcnt lgkmcnt(8)
	v_add_f32_e32 v210, v210, v211
	v_add_f32_e32 v212, v212, v213
	v_add_f32_e32 v214, v214, v215
	v_add_f32_e32 v216, v216, v217
	v_add_f32_e32 v210, v210, v212
	v_add_f32_e32 v214, v214, v216
	v_add_f32_e32 v185, v210, v214
	v_fmamk_f32 v185, v185, 0x3b800000, v207
	v_rsq_f32_e32 v210, v185
	v_add_u32_e32 v185, s24, v232
	v_pk_mul_f32 v[96:97], v[210:211], v[96:97] op_sel_hi:[0,1]
	v_pk_mul_f32 v[98:99], v[210:211], v[98:99] op_sel_hi:[0,1]
	v_pk_mul_f32 v[96:97], v[2:3], v[96:97]
	v_pk_mul_f32 v[98:99], v[4:5], v[98:99]
	v_cvt_pk_bf16_f32 v96, v96, v97
	v_cvt_pk_bf16_f32 v97, v98, v99
	v_pk_mul_f32 v[98:99], v[210:211], v[100:101] op_sel_hi:[0,1]
	v_pk_mul_f32 v[100:101], v[210:211], v[102:103] op_sel_hi:[0,1]
	v_pk_mul_f32 v[98:99], v[6:7], v[98:99]
	v_pk_mul_f32 v[100:101], v[8:9], v[100:101]
	v_cvt_pk_bf16_f32 v98, v98, v99
	v_cvt_pk_bf16_f32 v99, v100, v101
	ds_write2_b64 v185, v[96:97], v[98:99] offset1:2
	v_pk_mul_f32 v[96:97], v[210:211], v[104:105] op_sel_hi:[0,1]
	v_pk_mul_f32 v[98:99], v[210:211], v[106:107] op_sel_hi:[0,1]
	v_pk_mul_f32 v[96:97], v[10:11], v[96:97]
	v_pk_mul_f32 v[98:99], v[12:13], v[98:99]
	v_cvt_pk_bf16_f32 v96, v96, v97
	v_cvt_pk_bf16_f32 v97, v98, v99
	v_pk_mul_f32 v[98:99], v[210:211], v[108:109] op_sel_hi:[0,1]
	v_pk_mul_f32 v[100:101], v[210:211], v[110:111] op_sel_hi:[0,1]
	v_pk_mul_f32 v[98:99], v[112:113], v[98:99]
	v_pk_mul_f32 v[100:101], v[114:115], v[100:101]
	v_cvt_pk_bf16_f32 v98, v98, v99
	v_cvt_pk_bf16_f32 v99, v100, v101
	ds_write2_b64 v185, v[96:97], v[98:99] offset0:4 offset1:6
	s_waitcnt lgkmcnt(0)
	v_add_f32_e32 v246, v246, v247
	v_add_f32_e32 v248, v248, v249
	v_add_f32_e32 v250, v250, v251
	v_add_f32_e32 v252, v252, v253
	v_add_f32_e32 v246, v246, v248
	v_add_f32_e32 v250, v250, v252
	v_add_f32_e32 v96, v246, v250
	v_fmamk_f32 v96, v96, 0x3b800000, v207
	v_rsq_f32_e32 v96, v96
	s_nop 0
	v_pk_mul_f32 v[80:81], v[96:97], v[80:81] op_sel_hi:[0,1]
	v_pk_mul_f32 v[82:83], v[96:97], v[82:83] op_sel_hi:[0,1]
	v_pk_mul_f32 v[80:81], v[2:3], v[80:81]
	v_pk_mul_f32 v[82:83], v[4:5], v[82:83]
	v_cvt_pk_bf16_f32 v80, v80, v81
	v_cvt_pk_bf16_f32 v81, v82, v83
	v_pk_mul_f32 v[82:83], v[96:97], v[84:85] op_sel_hi:[0,1]
	v_pk_mul_f32 v[84:85], v[96:97], v[86:87] op_sel_hi:[0,1]
	v_pk_mul_f32 v[82:83], v[6:7], v[82:83]
	v_pk_mul_f32 v[84:85], v[8:9], v[84:85]
	v_cvt_pk_bf16_f32 v82, v82, v83
	v_cvt_pk_bf16_f32 v83, v84, v85
	ds_write2_b64 v177, v[80:81], v[82:83] offset1:2
	v_pk_mul_f32 v[80:81], v[96:97], v[88:89] op_sel_hi:[0,1]
	v_pk_mul_f32 v[82:83], v[96:97], v[90:91] op_sel_hi:[0,1]
	v_pk_mul_f32 v[80:81], v[10:11], v[80:81]
	v_pk_mul_f32 v[82:83], v[12:13], v[82:83]
	v_cvt_pk_bf16_f32 v80, v80, v81
	v_cvt_pk_bf16_f32 v81, v82, v83
	v_pk_mul_f32 v[82:83], v[96:97], v[92:93] op_sel_hi:[0,1]
	v_pk_mul_f32 v[84:85], v[96:97], v[94:95] op_sel_hi:[0,1]
	v_pk_mul_f32 v[82:83], v[112:113], v[82:83]
	v_pk_mul_f32 v[84:85], v[114:115], v[84:85]
	v_cvt_pk_bf16_f32 v82, v82, v83
	v_cvt_pk_bf16_f32 v83, v84, v85
	ds_write2_b64 v177, v[80:81], v[82:83] offset0:4 offset1:6
	s_cbranch_scc1 .LBB0_123
	s_bitcmp1_b32 s44, 0
	s_cselect_b32 s44, 0x8e00, 0
	s_add_i32 s61, s44, 0
	v_add_u32_e32 v80, s61, v14
	v_add_u32_e32 v81, v80, v15
	v_add_u32_e32 v80, v80, v165
	s_waitcnt vmcnt(16)
	ds_write_b128 v81, v[116:119]
	s_waitcnt vmcnt(15)
	ds_write_b128 v80, v[120:123]
	v_add_u32_e32 v80, s61, v172
	v_add_u32_e32 v81, v80, v173
	v_add_u32_e32 v80, v80, v228
	s_waitcnt vmcnt(14)
	ds_write_b128 v81, v[124:127] offset:18432
	s_waitcnt vmcnt(12)
	ds_write_b128 v80, v[128:131] offset:18432
	s_and_saveexec_b64 s[44:45], vcc
	v_add_u32_e32 v80, s61, v229
	ds_write_b32 v80, v1 offset:35840
	s_or_b64 exec, exec, s[44:45]
.LBB0_123:
	s_add_i32 s44, s54, s55
	s_ashr_i32 s45, s44, 31
	s_lshl_b64 s[44:45], s[44:45], 9
	s_or_b64 s[44:45], s[44:45], s[58:59]
	v_lshl_add_u64 v[80:81], s[44:45], 0, v[168:169]
	v_lshlrev_b64 v[80:81], 7, v[80:81]
	v_lshl_add_u64 v[82:83], s[44:45], 0, v[170:171]
	v_lshl_add_u64 v[80:81], v[166:167], 0, v[80:81]
	v_lshlrev_b64 v[82:83], 7, v[82:83]
	v_ashrrev_i32_e32 v185, 31, v184
	v_lshl_add_u64 v[82:83], v[166:167], 0, v[82:83]
	global_load_dwordx4 v[116:119], v[80:81], off
	global_load_dwordx4 v[120:123], v[82:83], off
	v_lshlrev_b64 v[80:81], 10, v[184:185]
	v_ashrrev_i32_e32 v183, 31, v182
	v_lshl_add_u64 v[80:81], v[174:175], 0, v[80:81]
	v_lshlrev_b64 v[82:83], 10, v[182:183]
	v_lshl_add_u64 v[82:83], v[174:175], 0, v[82:83]
	global_load_dwordx4 v[124:127], v[80:81], off
	global_load_dwordx4 v[128:131], v[82:83], off
	v_ashrrev_i32_e32 v187, 31, v186
	v_lshl_add_u64 v[80:81], v[186:187], 2, s[40:41]
	global_load_dword v1, v[80:81], off
	s_branch .LBB0_114

.LBB0_430:
	s_andn2_b64 vcc, exec, s[6:7]
	s_cbranch_vccnz .Lgemm_zero_skip
	s_add_u32 s46, s74, 0x80
	s_addc_u32 s47, s75, 0
	s_add_u32 s38, s78, 0x100
	s_addc_u32 s39, s79, 0
	s_mov_b32 s41, 0
.Lgemm_peel:
	s_add_i32 s48, s41, 2
	s_add_u32 s68, s46, 0x80
	s_addc_u32 s69, s47, 0
	s_add_i32 s93, 0, 0x10000
	s_cmp_eq_u32 s20, s41
	s_cselect_b32 s75, s81, s69
	s_cselect_b32 s74, s80, s68
	s_cselect_b32 s79, s77, s39
	s_cselect_b32 s78, s76, s38
	s_add_i32 s41, 0, 0x14000
	v_add_u32_e32 v156, s93, v177
	v_add_u32_e32 v172, s41, v177
	ds_read_b128 v[130:133], v156
	ds_read_b128 v[134:137], v156 offset:1024
	ds_read_b128 v[152:155], v156 offset:2048
	ds_read_b128 v[156:159], v156 offset:3072
	ds_read_b128 v[160:163], v172
	ds_read_b128 v[164:167], v172 offset:1024
	ds_read_b128 v[168:171], v172 offset:2048
	ds_read_b128 v[172:175], v172 offset:3072
	v_lshl_add_u64 v[204:205], s[46:47], 0, v[148:149]
	s_add_i32 m0, s0, 0xc000
	ds_read_b128 v[180:183], v178
	ds_read_b128 v[184:187], v178 offset:1024
	ds_read_b128 v[188:191], v178 offset:2048
	ds_read_b128 v[192:195], v178 offset:3072
	ds_read_b128 v[196:199], v178 offset:4096
	ds_read_b128 v[200:203], v178 offset:5120
	ds_read_b128 v[210:213], v178 offset:6144
	ds_read_b128 v[214:217], v178 offset:7168
	global_load_lds_dwordx4 v[204:205], off
	v_lshl_add_u64 v[204:205], s[46:47], 0, v[150:151]
	s_add_i32 m0, s0, 0xe000
	s_nop 0
	global_load_lds_dwordx4 v[204:205], off
	s_waitcnt vmcnt(8)
	s_waitcnt lgkmcnt(0)
	s_barrier
	s_setprio 1
	s_waitcnt lgkmcnt(0)
	v_mfma_f32_16x16x32_bf16 v[126:129], v[130:133], v[180:183], 0
	v_mfma_f32_16x16x32_bf16 v[122:125], v[152:155], v[180:183], 0
	v_mfma_f32_16x16x32_bf16 v[110:113], v[130:133], v[188:191], 0
	v_mfma_f32_16x16x32_bf16 v[106:109], v[152:155], v[188:191], 0
	v_mfma_f32_16x16x32_bf16 v[94:97], v[130:133], v[196:199], 0
	v_mfma_f32_16x16x32_bf16 v[90:93], v[152:155], v[196:199], 0
	v_mfma_f32_16x16x32_bf16 v[78:81], v[130:133], v[210:213], 0
	v_mfma_f32_16x16x32_bf16 v[74:77], v[152:155], v[210:213], 0
	v_mfma_f32_16x16x32_bf16 v[126:129], v[134:137], v[184:187], v[126:129]
	v_mfma_f32_16x16x32_bf16 v[122:125], v[156:159], v[184:187], v[122:125]
	v_mfma_f32_16x16x32_bf16 v[110:113], v[134:137], v[192:195], v[110:113]
	v_mfma_f32_16x16x32_bf16 v[106:109], v[156:159], v[192:195], v[106:109]
	v_mfma_f32_16x16x32_bf16 v[94:97], v[134:137], v[200:203], v[94:97]
	v_mfma_f32_16x16x32_bf16 v[90:93], v[156:159], v[200:203], v[90:93]
	v_mfma_f32_16x16x32_bf16 v[78:81], v[134:137], v[214:217], v[78:81]
	v_mfma_f32_16x16x32_bf16 v[74:77], v[156:159], v[214:217], v[74:77]
	s_setprio 0
	s_setprio 1
	v_mfma_f32_16x16x32_bf16 v[118:121], v[160:163], v[180:183], 0
	v_mfma_f32_16x16x32_bf16 v[114:117], v[168:171], v[180:183], 0
	v_mfma_f32_16x16x32_bf16 v[102:105], v[160:163], v[188:191], 0
	v_mfma_f32_16x16x32_bf16 v[98:101], v[168:171], v[188:191], 0
	v_mfma_f32_16x16x32_bf16 v[86:89], v[160:163], v[196:199], 0
	v_mfma_f32_16x16x32_bf16 v[82:85], v[168:171], v[196:199], 0
	v_mfma_f32_16x16x32_bf16 v[70:73], v[160:163], v[210:213], 0
	v_mfma_f32_16x16x32_bf16 v[66:69], v[168:171], v[210:213], 0
	v_mfma_f32_16x16x32_bf16 v[118:121], v[164:167], v[184:187], v[118:121]
	v_mfma_f32_16x16x32_bf16 v[114:117], v[172:175], v[184:187], v[114:117]
	v_mfma_f32_16x16x32_bf16 v[102:105], v[164:167], v[192:195], v[102:105]
	v_mfma_f32_16x16x32_bf16 v[98:101], v[172:175], v[192:195], v[98:101]
	v_mfma_f32_16x16x32_bf16 v[86:89], v[164:167], v[200:203], v[86:89]
	v_mfma_f32_16x16x32_bf16 v[82:85], v[172:175], v[200:203], v[82:85]
	v_mfma_f32_16x16x32_bf16 v[70:73], v[164:167], v[214:217], v[70:73]
	v_mfma_f32_16x16x32_bf16 v[66:69], v[172:175], v[214:217], v[66:69]
	s_setprio 0
	s_barrier
	s_add_i32 s68, s93, s91
	v_lshl_add_u64 v[204:205], s[78:79], 0, v[140:141]
	s_mov_b32 m0, s68
	ds_read_b128 v[180:183], v178 offset:16384
	ds_read_b128 v[184:187], v178 offset:17408
	ds_read_b128 v[188:191], v178 offset:18432
	ds_read_b128 v[192:195], v178 offset:19456
	ds_read_b128 v[196:199], v178 offset:20480
	ds_read_b128 v[200:203], v178 offset:21504
	ds_read_b128 v[210:213], v178 offset:22528
	ds_read_b128 v[214:217], v178 offset:23552
	global_load_lds_dwordx4 v[204:205], off
	s_add_i32 m0, s68, 0x2000
	v_lshl_add_u64 v[228:229], s[78:79], 0, v[144:145]
	s_add_u32 s78, s78, s58
	s_addc_u32 s79, s79, 0
	s_add_i32 s41, s41, s91
	global_load_lds_dwordx4 v[228:229], off
	v_lshl_add_u64 v[230:231], s[78:79], 0, v[140:141]
	s_mov_b32 m0, s41
	v_lshl_add_u64 v[232:233], s[78:79], 0, v[144:145]
	global_load_lds_dwordx4 v[230:231], off
	s_add_i32 m0, s41, 0x2000
	v_lshl_add_u64 v[234:235], s[74:75], 0, v[138:139]
	global_load_lds_dwordx4 v[232:233], off
	s_mov_b32 m0, s0
	v_lshl_add_u64 v[236:237], s[74:75], 0, v[142:143]
	global_load_lds_dwordx4 v[234:235], off
	s_mov_b32 m0, s1
	s_nop 0
	global_load_lds_dwordx4 v[236:237], off
	s_waitcnt vmcnt(8)
	s_waitcnt lgkmcnt(0)
	s_barrier
	s_setprio 1
	s_waitcnt lgkmcnt(0)
	v_mfma_f32_16x16x32_bf16 v[62:65], v[130:133], v[180:183], 0
	v_mfma_f32_16x16x32_bf16 v[58:61], v[152:155], v[180:183], 0
	v_mfma_f32_16x16x32_bf16 v[46:49], v[130:133], v[188:191], 0
	v_mfma_f32_16x16x32_bf16 v[42:45], v[152:155], v[188:191], 0
	v_mfma_f32_16x16x32_bf16 v[30:33], v[130:133], v[196:199], 0
	v_mfma_f32_16x16x32_bf16 v[26:29], v[152:155], v[196:199], 0
	v_mfma_f32_16x16x32_bf16 v[14:17], v[130:133], v[210:213], 0
	v_mfma_f32_16x16x32_bf16 v[10:13], v[152:155], v[210:213], 0
	v_mfma_f32_16x16x32_bf16 v[62:65], v[134:137], v[184:187], v[62:65]
	v_mfma_f32_16x16x32_bf16 v[58:61], v[156:159], v[184:187], v[58:61]
	v_mfma_f32_16x16x32_bf16 v[46:49], v[134:137], v[192:195], v[46:49]
	v_mfma_f32_16x16x32_bf16 v[42:45], v[156:159], v[192:195], v[42:45]
	v_mfma_f32_16x16x32_bf16 v[30:33], v[134:137], v[200:203], v[30:33]
	v_mfma_f32_16x16x32_bf16 v[26:29], v[156:159], v[200:203], v[26:29]
	v_mfma_f32_16x16x32_bf16 v[14:17], v[134:137], v[214:217], v[14:17]
	v_mfma_f32_16x16x32_bf16 v[10:13], v[156:159], v[214:217], v[10:13]
	s_setprio 0
	s_setprio 1
	v_mfma_f32_16x16x32_bf16 v[54:57], v[160:163], v[180:183], 0
	v_mfma_f32_16x16x32_bf16 v[50:53], v[168:171], v[180:183], 0
	v_mfma_f32_16x16x32_bf16 v[38:41], v[160:163], v[188:191], 0
	v_mfma_f32_16x16x32_bf16 v[34:37], v[168:171], v[188:191], 0
	v_mfma_f32_16x16x32_bf16 v[22:25], v[160:163], v[196:199], 0
	v_mfma_f32_16x16x32_bf16 v[18:21], v[168:171], v[196:199], 0
	v_mfma_f32_16x16x32_bf16 v[6:9], v[160:163], v[210:213], 0
	v_mfma_f32_16x16x32_bf16 v[2:5], v[168:171], v[210:213], 0
	v_mfma_f32_16x16x32_bf16 v[54:57], v[164:167], v[184:187], v[54:57]
	v_mfma_f32_16x16x32_bf16 v[50:53], v[172:175], v[184:187], v[50:53]
	v_mfma_f32_16x16x32_bf16 v[38:41], v[164:167], v[192:195], v[38:41]
	v_mfma_f32_16x16x32_bf16 v[34:37], v[172:175], v[192:195], v[34:37]
	v_mfma_f32_16x16x32_bf16 v[22:25], v[164:167], v[200:203], v[22:25]
	v_mfma_f32_16x16x32_bf16 v[18:21], v[172:175], v[200:203], v[18:21]
	v_mfma_f32_16x16x32_bf16 v[6:9], v[164:167], v[214:217], v[6:9]
	v_mfma_f32_16x16x32_bf16 v[2:5], v[172:175], v[214:217], v[2:5]
	s_setprio 0
	s_barrier
	s_add_i32 s41, 0, 0x18000
	s_add_i32 s68, 0, 0x1c000
	v_add_u32_e32 v156, s41, v177
	v_add_u32_e32 v172, s68, v177
	ds_read_b128 v[130:133], v156
	ds_read_b128 v[134:137], v156 offset:1024
	ds_read_b128 v[152:155], v156 offset:2048
	ds_read_b128 v[156:159], v156 offset:3072
	ds_read_b128 v[160:163], v172
	ds_read_b128 v[164:167], v172 offset:1024
	ds_read_b128 v[168:171], v172 offset:2048
	ds_read_b128 v[172:175], v172 offset:3072
	s_add_u32 s74, s74, s58
	s_addc_u32 s75, s75, 0
	s_mov_b32 m0, s72
	v_lshl_add_u64 v[238:239], s[74:75], 0, v[138:139]
	ds_read_b128 v[180:183], v178 offset:32768
	ds_read_b128 v[184:187], v178 offset:33792
	ds_read_b128 v[188:191], v178 offset:34816
	ds_read_b128 v[192:195], v178 offset:35840
	ds_read_b128 v[196:199], v178 offset:36864
	ds_read_b128 v[200:203], v178 offset:37888
	ds_read_b128 v[210:213], v178 offset:38912
	ds_read_b128 v[214:217], v178 offset:39936
	global_load_lds_dwordx4 v[238:239], off
	v_lshl_add_u64 v[238:239], s[74:75], 0, v[142:143]
	s_mov_b32 m0, s73
	s_nop 0
	global_load_lds_dwordx4 v[238:239], off
	s_waitcnt vmcnt(8)
	s_waitcnt lgkmcnt(0)
	s_barrier
	s_setprio 1
	s_waitcnt lgkmcnt(0)
	v_mfma_f32_16x16x32_bf16 v[126:129], v[130:133], v[180:183], v[126:129]
	v_mfma_f32_16x16x32_bf16 v[122:125], v[152:155], v[180:183], v[122:125]
	v_mfma_f32_16x16x32_bf16 v[110:113], v[130:133], v[188:191], v[110:113]
	v_mfma_f32_16x16x32_bf16 v[106:109], v[152:155], v[188:191], v[106:109]
	v_mfma_f32_16x16x32_bf16 v[94:97], v[130:133], v[196:199], v[94:97]
	v_mfma_f32_16x16x32_bf16 v[90:93], v[152:155], v[196:199], v[90:93]
	v_mfma_f32_16x16x32_bf16 v[78:81], v[130:133], v[210:213], v[78:81]
	v_mfma_f32_16x16x32_bf16 v[74:77], v[152:155], v[210:213], v[74:77]
	v_mfma_f32_16x16x32_bf16 v[126:129], v[134:137], v[184:187], v[126:129]
	v_mfma_f32_16x16x32_bf16 v[122:125], v[156:159], v[184:187], v[122:125]
	v_mfma_f32_16x16x32_bf16 v[110:113], v[134:137], v[192:195], v[110:113]
	v_mfma_f32_16x16x32_bf16 v[106:109], v[156:159], v[192:195], v[106:109]
	v_mfma_f32_16x16x32_bf16 v[94:97], v[134:137], v[200:203], v[94:97]
	v_mfma_f32_16x16x32_bf16 v[90:93], v[156:159], v[200:203], v[90:93]
	v_mfma_f32_16x16x32_bf16 v[78:81], v[134:137], v[214:217], v[78:81]
	v_mfma_f32_16x16x32_bf16 v[74:77], v[156:159], v[214:217], v[74:77]
	s_setprio 0
	s_setprio 1
	v_mfma_f32_16x16x32_bf16 v[118:121], v[160:163], v[180:183], v[118:121]
	v_mfma_f32_16x16x32_bf16 v[114:117], v[168:171], v[180:183], v[114:117]
	v_mfma_f32_16x16x32_bf16 v[102:105], v[160:163], v[188:191], v[102:105]
	v_mfma_f32_16x16x32_bf16 v[98:101], v[168:171], v[188:191], v[98:101]
	v_mfma_f32_16x16x32_bf16 v[86:89], v[160:163], v[196:199], v[86:89]
	v_mfma_f32_16x16x32_bf16 v[82:85], v[168:171], v[196:199], v[82:85]
	v_mfma_f32_16x16x32_bf16 v[70:73], v[160:163], v[210:213], v[70:73]
	v_mfma_f32_16x16x32_bf16 v[66:69], v[168:171], v[210:213], v[66:69]
	v_mfma_f32_16x16x32_bf16 v[118:121], v[164:167], v[184:187], v[118:121]
	v_mfma_f32_16x16x32_bf16 v[114:117], v[172:175], v[184:187], v[114:117]
	v_mfma_f32_16x16x32_bf16 v[102:105], v[164:167], v[192:195], v[102:105]
	v_mfma_f32_16x16x32_bf16 v[98:101], v[172:175], v[192:195], v[98:101]
	v_mfma_f32_16x16x32_bf16 v[86:89], v[164:167], v[200:203], v[86:89]
	v_mfma_f32_16x16x32_bf16 v[82:85], v[172:175], v[200:203], v[82:85]
	v_mfma_f32_16x16x32_bf16 v[70:73], v[164:167], v[214:217], v[70:73]
	v_mfma_f32_16x16x32_bf16 v[66:69], v[172:175], v[214:217], v[66:69]
	s_setprio 0
	s_barrier
	s_add_i32 s41, s41, s91
	v_lshl_add_u64 v[204:205], v[204:205], 0, s[18:19]
	s_mov_b32 m0, s41
	ds_read_b128 v[180:183], v178 offset:49152
	ds_read_b128 v[184:187], v178 offset:50176
	ds_read_b128 v[188:191], v178 offset:51200
	ds_read_b128 v[192:195], v178 offset:52224
	ds_read_b128 v[196:199], v178 offset:53248
	ds_read_b128 v[200:203], v178 offset:54272
	ds_read_b128 v[210:213], v178 offset:55296
	ds_read_b128 v[214:217], v178 offset:56320
	global_load_lds_dwordx4 v[204:205], off
	v_lshl_add_u64 v[204:205], v[228:229], 0, s[18:19]
	s_add_i32 m0, s41, 0x2000
	s_add_i32 s41, s68, s91
	global_load_lds_dwordx4 v[204:205], off
	v_lshl_add_u64 v[204:205], v[230:231], 0, s[18:19]
	s_mov_b32 m0, s41
	s_nop 0
	global_load_lds_dwordx4 v[204:205], off
	v_lshl_add_u64 v[204:205], v[232:233], 0, s[18:19]
	s_add_i32 m0, s41, 0x2000
	s_nop 0
	global_load_lds_dwordx4 v[204:205], off
	v_lshl_add_u64 v[204:205], v[234:235], 0, s[18:19]
	s_mov_b32 m0, s27
	s_nop 0
	global_load_lds_dwordx4 v[204:205], off
	v_lshl_add_u64 v[204:205], v[236:237], 0, s[18:19]
	s_mov_b32 m0, s25
	s_nop 0
	global_load_lds_dwordx4 v[204:205], off
	s_waitcnt vmcnt(8)
	s_waitcnt lgkmcnt(0)
	s_barrier
	s_setprio 1
	s_waitcnt lgkmcnt(0)
	v_mfma_f32_16x16x32_bf16 v[62:65], v[130:133], v[180:183], v[62:65]
	v_mfma_f32_16x16x32_bf16 v[58:61], v[152:155], v[180:183], v[58:61]
	v_mfma_f32_16x16x32_bf16 v[46:49], v[130:133], v[188:191], v[46:49]
	v_mfma_f32_16x16x32_bf16 v[42:45], v[152:155], v[188:191], v[42:45]
	v_mfma_f32_16x16x32_bf16 v[30:33], v[130:133], v[196:199], v[30:33]
	v_mfma_f32_16x16x32_bf16 v[26:29], v[152:155], v[196:199], v[26:29]
	v_mfma_f32_16x16x32_bf16 v[14:17], v[130:133], v[210:213], v[14:17]
	v_mfma_f32_16x16x32_bf16 v[10:13], v[152:155], v[210:213], v[10:13]
	v_mfma_f32_16x16x32_bf16 v[62:65], v[134:137], v[184:187], v[62:65]
	v_mfma_f32_16x16x32_bf16 v[58:61], v[156:159], v[184:187], v[58:61]
	v_mfma_f32_16x16x32_bf16 v[46:49], v[134:137], v[192:195], v[46:49]
	v_mfma_f32_16x16x32_bf16 v[42:45], v[156:159], v[192:195], v[42:45]
	v_mfma_f32_16x16x32_bf16 v[30:33], v[134:137], v[200:203], v[30:33]
	v_mfma_f32_16x16x32_bf16 v[26:29], v[156:159], v[200:203], v[26:29]
	v_mfma_f32_16x16x32_bf16 v[14:17], v[134:137], v[214:217], v[14:17]
	v_mfma_f32_16x16x32_bf16 v[10:13], v[156:159], v[214:217], v[10:13]
	s_setprio 0
	s_setprio 1
	v_mfma_f32_16x16x32_bf16 v[54:57], v[160:163], v[180:183], v[54:57]
	v_mfma_f32_16x16x32_bf16 v[50:53], v[168:171], v[180:183], v[50:53]
	v_mfma_f32_16x16x32_bf16 v[38:41], v[160:163], v[188:191], v[38:41]
	v_mfma_f32_16x16x32_bf16 v[34:37], v[168:171], v[188:191], v[34:37]
	v_mfma_f32_16x16x32_bf16 v[22:25], v[160:163], v[196:199], v[22:25]
	v_mfma_f32_16x16x32_bf16 v[18:21], v[168:171], v[196:199], v[18:21]
	v_mfma_f32_16x16x32_bf16 v[6:9], v[160:163], v[210:213], v[6:9]
	v_mfma_f32_16x16x32_bf16 v[2:5], v[168:171], v[210:213], v[2:5]
	v_mfma_f32_16x16x32_bf16 v[54:57], v[164:167], v[184:187], v[54:57]
	v_mfma_f32_16x16x32_bf16 v[50:53], v[172:175], v[184:187], v[50:53]
	v_mfma_f32_16x16x32_bf16 v[38:41], v[164:167], v[192:195], v[38:41]
	v_mfma_f32_16x16x32_bf16 v[34:37], v[172:175], v[192:195], v[34:37]
	v_mfma_f32_16x16x32_bf16 v[22:25], v[164:167], v[200:203], v[22:25]
	v_mfma_f32_16x16x32_bf16 v[18:21], v[172:175], v[200:203], v[18:21]
	v_mfma_f32_16x16x32_bf16 v[6:9], v[164:167], v[214:217], v[6:9]
	v_mfma_f32_16x16x32_bf16 v[2:5], v[172:175], v[214:217], v[2:5]
	s_setprio 0
	s_barrier
	s_add_u32 s46, s46, 0x100
	s_addc_u32 s47, s47, 0
	s_add_u32 s38, s38, 0x100
	s_addc_u32 s39, s39, 0
	s_cmp_ge_u32 s48, s50
	s_mov_b32 s41, s48
	s_cbranch_scc1 .LBB0_433

.Lgemm_zero_skip:
	v_mov_b32_e32 v129, 0
	v_mov_b32_e32 v128, v129
	v_mov_b32_e32 v127, v129
	v_mov_b32_e32 v126, v129
	v_mov_b32_e32 v125, v129
	v_mov_b32_e32 v124, v129
	v_mov_b32_e32 v123, v129
	v_mov_b32_e32 v122, v129
	v_mov_b32_e32 v113, v129
	v_mov_b32_e32 v112, v129
	v_mov_b32_e32 v111, v129
	v_mov_b32_e32 v110, v129
	v_mov_b32_e32 v109, v129
	v_mov_b32_e32 v108, v129
	v_mov_b32_e32 v107, v129
	v_mov_b32_e32 v106, v129
	v_mov_b32_e32 v97, v129
	v_mov_b32_e32 v96, v129
	v_mov_b32_e32 v95, v129
	v_mov_b32_e32 v94, v129
	v_mov_b32_e32 v93, v129
	v_mov_b32_e32 v92, v129
	v_mov_b32_e32 v91, v129
	v_mov_b32_e32 v90, v129
	v_mov_b32_e32 v81, v129
	v_mov_b32_e32 v80, v129
	v_mov_b32_e32 v79, v129
	v_mov_b32_e32 v78, v129
	v_mov_b32_e32 v77, v129
	v_mov_b32_e32 v76, v129
	v_mov_b32_e32 v75, v129
	v_mov_b32_e32 v74, v129
	v_mov_b32_e32 v121, v129
	v_mov_b32_e32 v120, v129
	v_mov_b32_e32 v119, v129
	v_mov_b32_e32 v118, v129
	v_mov_b32_e32 v117, v129
	v_mov_b32_e32 v116, v129
	v_mov_b32_e32 v115, v129
	v_mov_b32_e32 v114, v129
	v_mov_b32_e32 v105, v129
	v_mov_b32_e32 v104, v129
	v_mov_b32_e32 v103, v129
	v_mov_b32_e32 v102, v129
	v_mov_b32_e32 v101, v129
	v_mov_b32_e32 v100, v129
	v_mov_b32_e32 v99, v129
	v_mov_b32_e32 v98, v129
	v_mov_b32_e32 v89, v129
	v_mov_b32_e32 v88, v129
	v_mov_b32_e32 v87, v129
	v_mov_b32_e32 v86, v129
	v_mov_b32_e32 v85, v129
	v_mov_b32_e32 v84, v129
	v_mov_b32_e32 v83, v129
	v_mov_b32_e32 v82, v129
	v_mov_b32_e32 v73, v129
	v_mov_b32_e32 v72, v129
	v_mov_b32_e32 v71, v129
	v_mov_b32_e32 v70, v129
	v_mov_b32_e32 v69, v129
	v_mov_b32_e32 v68, v129
	v_mov_b32_e32 v67, v129
	v_mov_b32_e32 v66, v129
	v_mov_b32_e32 v65, v129
	v_mov_b32_e32 v64, v129
	v_mov_b32_e32 v63, v129
	v_mov_b32_e32 v62, v129
	v_mov_b32_e32 v61, v129
	v_mov_b32_e32 v60, v129
	v_mov_b32_e32 v59, v129
	v_mov_b32_e32 v58, v129
	v_mov_b32_e32 v49, v129
	v_mov_b32_e32 v48, v129
	v_mov_b32_e32 v47, v129
	v_mov_b32_e32 v46, v129
	v_mov_b32_e32 v45, v129
	v_mov_b32_e32 v44, v129
	v_mov_b32_e32 v43, v129
	v_mov_b32_e32 v42, v129
	v_mov_b32_e32 v33, v129
	v_mov_b32_e32 v32, v129
	v_mov_b32_e32 v31, v129
	v_mov_b32_e32 v30, v129
	v_mov_b32_e32 v29, v129
	v_mov_b32_e32 v28, v129
	v_mov_b32_e32 v27, v129
	v_mov_b32_e32 v26, v129
	v_mov_b32_e32 v17, v129
	v_mov_b32_e32 v16, v129
	v_mov_b32_e32 v15, v129
	v_mov_b32_e32 v14, v129
	v_mov_b32_e32 v13, v129
	v_mov_b32_e32 v12, v129
	v_mov_b32_e32 v11, v129
	v_mov_b32_e32 v10, v129
	v_mov_b32_e32 v57, v129
	v_mov_b32_e32 v56, v129
	v_mov_b32_e32 v55, v129
	v_mov_b32_e32 v54, v129
	v_mov_b32_e32 v53, v129
	v_mov_b32_e32 v52, v129
	v_mov_b32_e32 v51, v129
	v_mov_b32_e32 v50, v129
	v_mov_b32_e32 v41, v129
	v_mov_b32_e32 v40, v129
	v_mov_b32_e32 v39, v129
	v_mov_b32_e32 v38, v129
	v_mov_b32_e32 v37, v129
	v_mov_b32_e32 v36, v129
	v_mov_b32_e32 v35, v129
	v_mov_b32_e32 v34, v129
	v_mov_b32_e32 v25, v129
	v_mov_b32_e32 v24, v129
	v_mov_b32_e32 v23, v129
	v_mov_b32_e32 v22, v129
	v_mov_b32_e32 v21, v129
	v_mov_b32_e32 v20, v129
	v_mov_b32_e32 v19, v129
	v_mov_b32_e32 v18, v129
	v_mov_b32_e32 v9, v129
	v_mov_b32_e32 v8, v129
	v_mov_b32_e32 v7, v129
	v_mov_b32_e32 v6, v129
	v_mov_b32_e32 v5, v129
	v_mov_b32_e32 v4, v129
	v_mov_b32_e32 v3, v129
	v_mov_b32_e32 v2, v129
	s_branch .LBB0_433
